# v31 + phase-4 elementwise loop (group norm, bonus, gate): next trip's eight row loads issued one trip ahead into spare registers, copied at the trip top
# speedup vs baseline: 1.0052x; 1.0052x over previous
; __device__ __forceinline__ int tid_v() { int t = threadIdx.x; asm volatile("" : "+v"(t)); return t; }
; __device__ __forceinline__ int bid_s() { int b = blockIdx.x; asm volatile("" : "+s"(b)); return b; }
; __device__ __forceinline__ void phase4(int l, unsigned char* shm) {
;     ...
;     const int lane = tid_v() & 63, gw = bid_s() * 8 + (tid_v() >> 6);
;     const float* lnw = IN(15) + l * 512; const float* lnb = IN(16) + l * 512; const float* hn = IN(22) + l * 512;
;     bf16_t* Y = B.br + VEC_STRIDE;
;     for (int mb = gw; mb < MS; mb += 4096) {
;         const int c0 = lane * 8, h = lane >> 3;
;         u32x4 yw[2], gwd[2], vwd[2]; float c3v[2];
; #pragma unroll
;         for (int u = 0; u < 2; ++u) { const size_t o = (size_t)(mb + 2048 * u) * 512 + c0; yw[u] = *(const u32x4*)(Y + o); gwd[u] = *(const u32x4*)(B.G + o); vwd[u] = *(const u32x4*)(B.V + o); c3v[u] = B.C3[(mb + 2048 * u) * 8 + h]; }
;         const f32x4 w0 = *(const f32x4*)(lnw + c0), w1 = *(const f32x4*)(lnw + c0 + 4), b0 = *(const f32x4*)(lnb + c0), b1 = *(const f32x4*)(lnb + c0 + 4);
.LBB0_814:
	s_or_b64 exec, exec, s[16:17]
	v_mov_b32_e32 v2, v179
	s_mov_b32 s27, s87
	s_waitcnt lgkmcnt(0)
	v_mov_b32_e32 v0, v179
	s_barrier
	s_load_dwordx2 s[22:23], s[0:1], 0x118
	s_waitcnt lgkmcnt(0)
	s_lshl_b32 s2, s27, 3
	s_movk_i32 s16, 0x4000
	v_ashrrev_i32_e32 v1, 6, v0
	v_add_u32_e32 v0, s2, v1
	s_load_dwordx2 s[2:3], s[0:1], 0x78
	s_waitcnt lgkmcnt(0)
	s_load_dwordx2 s[34:35], s[0:1], 0x80
	s_waitcnt lgkmcnt(0)
	s_load_dwordx2 s[20:21], s[0:1], 0xb0
	s_waitcnt lgkmcnt(0)
	s_lshl_b32 s30, s69, 9
	v_cmp_gt_i32_e32 vcc, s16, v0
	s_and_saveexec_b64 s[16:17], vcc
	s_cbranch_execz .LBB0_817
	s_add_u32 s18, s22, 0x8000000
	s_addc_u32 s19, s23, 0
	s_lshl_b64 s[36:37], s[30:31], 2
	s_add_u32 s34, s34, s36
	s_addc_u32 s35, s35, s37
	v_and_b32_e32 v3, 63, v2
	v_bfe_u32 v2, v2, 3, 3
	s_add_u32 s2, s2, s36
	v_lshl_or_b32 v2, s27, 6, v2
	s_addc_u32 s3, s3, s37
	v_lshlrev_b32_e32 v176, 5, v3
	s_waitcnt vmcnt(1)
	v_lshl_add_u32 v20, v1, 3, v2
	v_add_u32_e32 v2, 0x800, v0
	v_lshl_add_u64 v[16:17], s[2:3], 0, v[176:177]
	v_lshl_add_u64 v[18:19], s[34:35], 0, v[176:177]
	v_lshlrev_b32_e32 v176, 4, v3
	v_ashrrev_i32_e32 v3, 31, v2
	v_ashrrev_i32_e32 v1, 31, v0
	v_add_u32_e32 v31, 0xfffff000, v0
	v_lshlrev_b64 v[2:3], 10, v[2:3]
	v_lshlrev_b64 v[0:1], 10, v[0:1]
	v_lshl_add_u64 v[22:23], s[22:23], 0, v[2:3]
	s_waitcnt vmcnt(0)
	v_lshl_add_u64 v[24:25], s[22:23], 0, v[0:1]
	s_mov_b64 s[34:35], 0
	s_mov_b64 s[42:43], 0x1ac00000
	s_mov_b64 s[44:45], 0x18c00000
	s_mov_b64 s[46:47], 0x17c00000
	s_mov_b32 s36, 3
	v_mov_b64_e32 v[154:155], v[24:25]
	v_mov_b64_e32 v[156:157], v[22:23]
	v_mov_b32_e32 v158, v20
	v_mov_b32_e32 v159, 0
	v_mov_b32_e32 v123, 0
	v_lshl_add_u64 v[120:121], v[154:155], 0, v[176:177]
	v_lshl_add_u64 v[160:161], v[120:121], 0, s[42:43]
	v_lshl_add_u64 v[162:163], v[120:121], 0, s[44:45]
	v_lshl_add_u64 v[164:165], v[120:121], 0, s[46:47]
	v_lshl_add_u64 v[166:167], v[158:159], 2, s[18:19]
	global_load_dwordx4 v[128:131], v[160:161], off
	global_load_dwordx4 v[132:135], v[162:163], off
	global_load_dwordx4 v[136:139], v[164:165], off
	global_load_dword v152, v[166:167], off
	v_lshl_add_u64 v[120:121], v[156:157], 0, v[176:177]
	v_add_u32_e32 v122, 0x4000, v158
	v_lshl_add_u64 v[168:169], v[120:121], 0, s[42:43]
	v_lshl_add_u64 v[170:171], v[120:121], 0, s[44:45]
	v_lshl_add_u64 v[172:173], v[120:121], 0, s[46:47]
	v_lshl_add_u64 v[174:175], v[122:123], 2, s[18:19]
	global_load_dwordx4 v[140:143], v[168:169], off
	global_load_dwordx4 v[144:147], v[170:171], off
	global_load_dwordx4 v[148:151], v[172:173], off
	global_load_dword v153, v[174:175], off
	s_cmp_lg_u32 s36, 0
	s_cselect_b32 s38, s62, 0
	s_cselect_b32 s39, s63, 0
	s_cselect_b32 s37, 0x8000, 0
	s_sub_i32 s36, s36, 1
	s_max_i32 s36, s36, 0
	v_lshl_add_u64 v[154:155], v[154:155], 0, s[38:39]
	v_lshl_add_u64 v[156:157], v[156:157], 0, s[38:39]
	v_add_u32_e32 v158, s37, v158
	s_waitcnt vmcnt(0)
.LBB0_816:
	s_waitcnt vmcnt(2)
	v_mov_b64_e32 v[50:51], v[128:129]
	v_mov_b64_e32 v[52:53], v[130:131]
	v_mov_b64_e32 v[34:35], v[132:133]
	v_mov_b64_e32 v[36:37], v[134:135]
	v_mov_b64_e32 v[42:43], v[136:137]
	v_mov_b64_e32 v[44:45], v[138:139]
	v_mov_b32_e32 v30, v152
	v_mov_b64_e32 v[54:55], v[140:141]
	v_mov_b64_e32 v[56:57], v[142:143]
	v_mov_b64_e32 v[58:59], v[144:145]
	v_mov_b64_e32 v[60:61], v[146:147]
	v_mov_b64_e32 v[62:63], v[148:149]
	v_mov_b64_e32 v[64:65], v[150:151]
	v_mov_b32_e32 v32, v153
	v_lshl_add_u64 v[0:1], v[24:25], 0, v[176:177]
	v_add_co_u32_e32 v26, vcc, 0x1ac00000, v0
	v_ashrrev_i32_e32 v21, 31, v20
	s_nop 0
	v_addc_co_u32_e32 v27, vcc, 0, v1, vcc
	v_add_co_u32_e32 v2, vcc, 0x18c00000, v0
	s_nop 0
	s_nop 0
	v_addc_co_u32_e32 v3, vcc, 0, v1, vcc
	v_add_co_u32_e32 v0, vcc, 0x17c00000, v0
	s_nop 0
	s_nop 0
	v_addc_co_u32_e32 v1, vcc, 0, v1, vcc
	s_nop 0
	v_lshl_add_u64 v[0:1], v[20:21], 2, s[18:19]
	s_nop 0
	v_lshl_add_u64 v[0:1], v[22:23], 0, v[176:177]
	s_mov_b32 s2, 0x1ac00000
	v_add_co_u32_e32 v28, vcc, s2, v0
	s_mov_b32 s2, 0x18c00000
	s_nop 0
	v_addc_co_u32_e32 v29, vcc, 0, v1, vcc
	s_nop 0
	v_add_co_u32_e32 v2, vcc, s2, v0
	s_mov_b32 s2, 0x17c00000
	s_nop 0
	v_addc_co_u32_e32 v3, vcc, 0, v1, vcc
	v_add_co_u32_e32 v0, vcc, s2, v0
	s_nop 0
	s_nop 0
	v_addc_co_u32_e32 v1, vcc, 0, v1, vcc
	s_nop 0
	v_add_u32_e32 v0, 0x4000, v20
	v_ashrrev_i32_e32 v1, 31, v0
	v_lshl_add_u64 v[0:1], v[0:1], 2, s[18:19]
	s_nop 0
	s_nop 0
	global_load_dwordx4 v[0:3], v[16:17], off offset:16
	global_load_dwordx4 v[8:11], v[16:17], off
	global_load_dwordx4 v[4:7], v[18:19], off offset:16
	global_load_dwordx4 v[12:15], v[18:19], off
	s_mov_b32 s2, 0x3c800000
	v_add_u32_e32 v20, 0x8000, v20
	v_lshl_add_u64 v[22:23], v[22:23], 0, s[62:63]
	v_lshl_add_u64 v[24:25], v[24:25], 0, s[62:63]
	v_lshl_add_u64 v[120:121], v[154:155], 0, v[176:177]
	v_lshl_add_u64 v[160:161], v[120:121], 0, s[42:43]
	v_lshl_add_u64 v[162:163], v[120:121], 0, s[44:45]
	v_lshl_add_u64 v[164:165], v[120:121], 0, s[46:47]
	v_lshl_add_u64 v[166:167], v[158:159], 2, s[18:19]
	global_load_dwordx4 v[128:131], v[160:161], off
	global_load_dwordx4 v[132:135], v[162:163], off
	global_load_dwordx4 v[136:139], v[164:165], off
	global_load_dword v152, v[166:167], off
	v_lshl_add_u64 v[120:121], v[156:157], 0, v[176:177]
	v_add_u32_e32 v122, 0x4000, v158
	v_lshl_add_u64 v[168:169], v[120:121], 0, s[42:43]
	v_lshl_add_u64 v[170:171], v[120:121], 0, s[44:45]
	v_lshl_add_u64 v[172:173], v[120:121], 0, s[46:47]
	v_lshl_add_u64 v[174:175], v[122:123], 2, s[18:19]
	global_load_dwordx4 v[140:143], v[168:169], off
	global_load_dwordx4 v[144:147], v[170:171], off
	global_load_dwordx4 v[148:151], v[172:173], off
	global_load_dword v153, v[174:175], off
; __device__ __forceinline__ void unpack8(const u32x4& w, f32x4& v0, f32x4& v1) { v0[0] = bflo(w.x); v0[1] = bfhi(w.x); v0[2] = bflo(w.y); v0[3] = bfhi(w.y); v1[0] = bflo(w.z); v1[1] = bfhi(w.z); v1[2] = bflo(w.w); v1[3] = bfhi(w.w); }
; __device__ __forceinline__ float rsum8(float v) { v += dppf<0xB1>(v); v += dppf<0x4E>(v); v += dppf<0x141>(v); return v; }
; __device__ __forceinline__ void phase4(int l, unsigned char* shm) {
;     ...
; #pragma unroll
;         for (int u = 0; u < 2; ++u) {
;             const size_t o = (size_t)(mb + 2048 * u) * 512 + c0;
;             f32x4 y0, y1, g0, g1, v0, v1;
;             unpack8(yw[u], y0, y1); unpack8(gwd[u], g0, g1); unpack8(vwd[u], v0, v1);
;             const float c3 = c3v[u];
;             const float mean = rsum8((y0[0] + y0[1]) + (y0[2] + y0[3]) + (y1[0] + y1[1]) + (y1[2] + y1[3])) * (1.0f / 64.0f);
;             const f32x4 d0 = y0 - mean, d1 = y1 - mean;
;             const float var = rsum8(d0[0] * d0[0] + d0[1] * d0[1] + d0[2] * d0[2] + d0[3] * d0[3] + d1[0] * d1[0] + d1[1] * d1[1] + d1[2] * d1[2] + d1[3] * d1[3]) * (1.0f / 64.0f);
;             const float rstd = rsqrtf(var + 64e-5f);
	s_cmp_lg_u32 s36, 0
	s_cselect_b32 s38, s62, 0
	s_cselect_b32 s39, s63, 0
	s_cselect_b32 s37, 0x8000, 0
	s_sub_i32 s36, s36, 1
	s_max_i32 s36, s36, 0
	v_lshl_add_u64 v[154:155], v[154:155], 0, s[38:39]
	v_lshl_add_u64 v[156:157], v[156:157], 0, s[38:39]
	v_add_u32_e32 v158, s37, v158
	v_lshlrev_b32_e32 v67, 16, v51
	v_lshlrev_b32_e32 v66, 16, v50
	v_and_b32_e32 v51, 0xffff0000, v51
	v_and_b32_e32 v50, 0xffff0000, v50
	v_pk_add_f32 v[68:69], v[66:67], v[50:51]
	v_lshlrev_b32_e32 v71, 16, v53
	v_lshlrev_b32_e32 v70, 16, v52
	v_and_b32_e32 v53, 0xffff0000, v53
	v_and_b32_e32 v52, 0xffff0000, v52
	v_pk_add_f32 v[72:73], v[70:71], v[52:53]
	v_add_f32_e32 v21, v68, v69
	v_add_f32_e32 v21, v72, v21
	v_add_f32_e32 v21, v73, v21
	v_lshlrev_b32_e32 v46, 16, v42
	v_and_b32_e32 v47, 0xffff0000, v42
	v_add_f32_dpp v21, v21, v21 quad_perm:[1,0,3,2] row_mask:0xf bank_mask:0xf bound_ctrl:1
	v_lshlrev_b32_e32 v48, 16, v43
	v_and_b32_e32 v49, 0xffff0000, v43
	v_add_f32_dpp v21, v21, v21 quad_perm:[2,3,0,1] row_mask:0xf bank_mask:0xf bound_ctrl:1
	v_lshlrev_b32_e32 v87, 16, v55
	v_lshlrev_b32_e32 v86, 16, v54
	v_and_b32_e32 v55, 0xffff0000, v55
	v_and_b32_e32 v54, 0xffff0000, v54
	v_add_f32_dpp v21, v21, v21 row_half_mirror row_mask:0xf bank_mask:0xf bound_ctrl:1
	v_pk_add_f32 v[88:89], v[86:87], v[54:55]
	v_lshlrev_b32_e32 v91, 16, v57
	v_lshlrev_b32_e32 v90, 16, v56
	v_and_b32_e32 v57, 0xffff0000, v57
	v_and_b32_e32 v56, 0xffff0000, v56
	v_fmac_f32_e32 v50, 0xbc800000, v21
	v_fmac_f32_e32 v66, 0xbc800000, v21
	v_fmac_f32_e32 v51, 0xbc800000, v21
	v_fmac_f32_e32 v67, 0xbc800000, v21
	v_fmac_f32_e32 v52, 0xbc800000, v21
	v_fmac_f32_e32 v70, 0xbc800000, v21
	v_fmac_f32_e32 v53, 0xbc800000, v21
	v_fmac_f32_e32 v71, 0xbc800000, v21
	v_pk_add_f32 v[92:93], v[90:91], v[56:57]
	v_add_f32_e32 v21, v88, v89
	v_add_f32_e32 v21, v92, v21
	v_add_f32_e32 v21, v93, v21
	v_mov_b32_e32 v68, v67
	v_mov_b32_e32 v67, v50
	v_add_f32_dpp v21, v21, v21 quad_perm:[1,0,3,2] row_mask:0xf bank_mask:0xf bound_ctrl:1
	v_mov_b32_e32 v69, v51
	v_pk_mul_f32 v[50:51], v[66:67], v[66:67]
	v_add_f32_dpp v21, v21, v21 quad_perm:[2,3,0,1] row_mask:0xf bank_mask:0xf bound_ctrl:1
	v_pk_mul_f32 v[72:73], v[68:69], v[68:69]
	v_mov_b32_e32 v95, v50
	v_add_f32_dpp v21, v21, v21 row_half_mirror row_mask:0xf bank_mask:0xf bound_ctrl:1
	v_fmac_f32_e32 v54, 0xbc800000, v21
	v_fmac_f32_e32 v87, 0xbc800000, v21
	v_fmac_f32_e32 v86, 0xbc800000, v21
	v_fmac_f32_e32 v55, 0xbc800000, v21
	v_mov_b32_e32 v88, v87
	v_mov_b32_e32 v87, v54
	v_mov_b32_e32 v89, v55
	v_pk_mul_f32 v[54:55], v[86:87], v[86:87]
	v_fmac_f32_e32 v56, 0xbc800000, v21
	v_fmac_f32_e32 v91, 0xbc800000, v21
	v_pk_mul_f32 v[92:93], v[88:89], v[88:89]
	v_mov_b32_e32 v94, v54
	v_mov_b32_e32 v50, v55
	v_mov_b32_e32 v74, v71
	v_mov_b32_e32 v71, v52
	v_fmac_f32_e32 v90, 0xbc800000, v21
	v_fmac_f32_e32 v57, 0xbc800000, v21
	v_pk_add_f32 v[50:51], v[94:95], v[50:51]
	v_mov_b32_e32 v54, v91
	v_mov_b32_e32 v91, v56
	v_mov_b32_e32 v96, v92
	v_mov_b32_e32 v97, v72
	v_mov_b32_e32 v75, v53
	v_pk_mul_f32 v[52:53], v[70:71], v[70:71]
	v_mov_b32_e32 v55, v57
	v_pk_mul_f32 v[56:57], v[90:91], v[90:91]
	v_pk_add_f32 v[50:51], v[96:97], v[50:51]
	v_mov_b32_e32 v72, v93
	v_pk_add_f32 v[50:51], v[72:73], v[50:51]
	v_mov_b32_e32 v72, v56
	v_mov_b32_e32 v73, v52
	v_pk_mul_f32 v[76:77], v[74:75], v[74:75]
	v_pk_mul_f32 v[94:95], v[54:55], v[54:55]
	v_pk_add_f32 v[50:51], v[72:73], v[50:51]
	v_mov_b32_e32 v52, v57
	v_pk_add_f32 v[50:51], v[52:53], v[50:51]
	v_mov_b32_e32 v52, v94
	v_mov_b32_e32 v53, v76
	v_pk_add_f32 v[50:51], v[52:53], v[50:51]
	v_mov_b32_e32 v76, v95
	v_pk_add_f32 v[50:51], v[76:77], v[50:51]
	v_lshlrev_b32_e32 v38, 16, v34
	v_and_b32_e32 v39, 0xffff0000, v34
	v_mov_b32_dpp v53, v51 quad_perm:[1,0,3,2] row_mask:0xf bank_mask:0xf bound_ctrl:1
	v_mov_b32_dpp v52, v50 quad_perm:[1,0,3,2] row_mask:0xf bank_mask:0xf bound_ctrl:1
	v_pk_add_f32 v[50:51], v[50:51], v[52:53]
	v_lshlrev_b32_e32 v40, 16, v35
	v_and_b32_e32 v41, 0xffff0000, v35
	v_mov_b32_dpp v53, v51 quad_perm:[2,3,0,1] row_mask:0xf bank_mask:0xf bound_ctrl:1
	v_mov_b32_dpp v52, v50 quad_perm:[2,3,0,1] row_mask:0xf bank_mask:0xf bound_ctrl:1
	v_pk_add_f32 v[50:51], v[50:51], v[52:53]
	v_lshlrev_b32_e32 v42, 16, v44
	v_and_b32_e32 v43, 0xffff0000, v44
	v_mov_b32_dpp v53, v51 row_half_mirror row_mask:0xf bank_mask:0xf bound_ctrl:1
	v_mov_b32_dpp v52, v50 row_half_mirror row_mask:0xf bank_mask:0xf bound_ctrl:1
	v_pk_add_f32 v[50:51], v[50:51], v[52:53]
	v_mov_b32_e32 v52, 0x3a27c5ac
	v_pk_fma_f32 v[50:51], v[50:51], s[2:3], v[52:53] op_sel_hi:[1,0,0]
	v_lshlrev_b32_e32 v44, 16, v45
	v_mul_f32_e32 v21, 0x4b800000, v51
	v_cmp_gt_f32_e64 s[40:41], s33, v51
	v_cmp_gt_f32_e32 vcc, s33, v50
	v_and_b32_e32 v45, 0xffff0000, v45
	v_cndmask_b32_e64 v21, v51, v21, s[40:41]
	v_rsq_f32_e32 v21, v21
	v_lshlrev_b32_e32 v34, 16, v36
	v_and_b32_e32 v35, 0xffff0000, v36
	v_lshlrev_b32_e32 v36, 16, v37
	v_mul_f32_e32 v33, 0x45800000, v21
	v_cndmask_b32_e64 v52, v21, v33, s[40:41]
	v_pk_mul_f32 v[56:57], v[66:67], v[52:53] op_sel_hi:[1,0]
	v_pk_mul_f32 v[66:67], v[68:69], v[52:53] op_sel_hi:[1,0]
	s_waitcnt vmcnt(8)
; __device__ __forceinline__ u32x4 pack8(const f32x4& v0, const f32x4& v1) { u32x4 w; w.x = cvt_pk_bf16(v0[0], v0[1]); w.y = cvt_pk_bf16(v0[2], v0[3]); w.z = cvt_pk_bf16(v1[0], v1[1]); w.w = cvt_pk_bf16(v1[2], v1[3]); return w; }
; __device__ __forceinline__ void phase4(int l, unsigned char* shm) {
;     ...
;             const f32x4 r0 = (d0 * rstd * w0 + b0 + c3 * v0) * g0, r1 = (d1 * rstd * w1 + b1 + c3 * v1) * g1;
;             *(u32x4*)(Y + o) = pack8(r0, r1);
;         }
;     }
	v_pk_fma_f32 v[56:57], v[8:9], v[56:57], v[12:13]
	v_pk_fma_f32 v[66:67], v[10:11], v[66:67], v[14:15]
	v_pk_fma_f32 v[46:47], v[30:31], v[46:47], v[56:57] op_sel_hi:[0,1,1]
	v_pk_fma_f32 v[48:49], v[30:31], v[48:49], v[66:67] op_sel_hi:[0,1,1]
	v_mul_f32_e32 v21, 0x4b800000, v50
	v_pk_mul_f32 v[40:41], v[48:49], v[40:41]
	v_pk_mul_f32 v[38:39], v[46:47], v[38:39]
	v_pk_mul_f32 v[46:47], v[70:71], v[52:53] op_sel_hi:[1,0]
	v_pk_mul_f32 v[48:49], v[74:75], v[52:53] op_sel_hi:[1,0]
	v_cndmask_b32_e32 v21, v50, v21, vcc
	v_pk_fma_f32 v[48:49], v[2:3], v[48:49], v[6:7]
	v_pk_fma_f32 v[46:47], v[0:1], v[46:47], v[4:5]
	v_rsq_f32_e32 v21, v21
	v_and_b32_e32 v37, 0xffff0000, v37
	v_pk_fma_f32 v[42:43], v[30:31], v[42:43], v[46:47] op_sel_hi:[0,1,1]
	v_pk_fma_f32 v[44:45], v[30:31], v[44:45], v[48:49] op_sel_hi:[0,1,1]
	v_pk_mul_f32 v[44:45], v[44:45], v[36:37]
	v_pk_mul_f32 v[36:37], v[42:43], v[34:35]
	v_cvt_pk_bf16_f32 v34, v38, v39
	v_cvt_pk_bf16_f32 v35, v40, v41
	v_cvt_pk_bf16_f32 v36, v36, v37
	v_cvt_pk_bf16_f32 v37, v44, v45
	global_store_dwordx4 v[26:27], v[34:37], off
	v_mul_f32_e32 v26, 0x45800000, v21
	v_cndmask_b32_e32 v26, v21, v26, vcc
	v_pk_mul_f32 v[34:35], v[86:87], v[26:27] op_sel_hi:[1,0]
	v_pk_mul_f32 v[36:37], v[88:89], v[26:27] op_sel_hi:[1,0]
	v_pk_fma_f32 v[8:9], v[8:9], v[34:35], v[12:13]
	v_pk_fma_f32 v[10:11], v[10:11], v[36:37], v[14:15]
	v_pk_mul_f32 v[12:13], v[90:91], v[26:27] op_sel_hi:[1,0]
	v_pk_mul_f32 v[14:15], v[54:55], v[26:27] op_sel_hi:[1,0]
	v_lshlrev_b32_e32 v82, 16, v62
	v_and_b32_e32 v83, 0xffff0000, v62
	v_lshlrev_b32_e32 v62, 16, v63
	v_and_b32_e32 v63, 0xffff0000, v63
	v_lshlrev_b32_e32 v84, 16, v64
	v_and_b32_e32 v85, 0xffff0000, v64
	v_lshlrev_b32_e32 v64, 16, v65
	v_and_b32_e32 v65, 0xffff0000, v65
	v_pk_fma_f32 v[2:3], v[2:3], v[14:15], v[6:7]
	v_pk_fma_f32 v[0:1], v[0:1], v[12:13], v[4:5]
	v_lshlrev_b32_e32 v78, 16, v58
	v_and_b32_e32 v79, 0xffff0000, v58
	v_lshlrev_b32_e32 v58, 16, v59
	v_and_b32_e32 v59, 0xffff0000, v59
	v_lshlrev_b32_e32 v80, 16, v60
	v_and_b32_e32 v81, 0xffff0000, v60
	v_lshlrev_b32_e32 v60, 16, v61
	v_and_b32_e32 v61, 0xffff0000, v61
	v_pk_fma_f32 v[8:9], v[32:33], v[82:83], v[8:9] op_sel_hi:[0,1,1]
	v_pk_fma_f32 v[10:11], v[32:33], v[62:63], v[10:11] op_sel_hi:[0,1,1]
	v_pk_fma_f32 v[0:1], v[32:33], v[84:85], v[0:1] op_sel_hi:[0,1,1]
	v_pk_fma_f32 v[2:3], v[32:33], v[64:65], v[2:3] op_sel_hi:[0,1,1]
	v_add_u32_e32 v31, 0x1000, v31
	v_pk_mul_f32 v[10:11], v[10:11], v[58:59]
	v_pk_mul_f32 v[8:9], v[8:9], v[78:79]
	v_pk_mul_f32 v[4:5], v[2:3], v[60:61]
	v_pk_mul_f32 v[2:3], v[0:1], v[80:81]
	v_cmp_lt_i32_e32 vcc, s58, v31
	v_cvt_pk_bf16_f32 v0, v8, v9
	v_cvt_pk_bf16_f32 v1, v10, v11
	v_cvt_pk_bf16_f32 v2, v2, v3
	v_cvt_pk_bf16_f32 v3, v4, v5
	s_or_b64 s[34:35], vcc, s[34:35]
	global_store_dwordx4 v[28:29], v[0:3], off
	s_andn2_b64 exec, exec, s[34:35]
	s_cbranch_execnz .LBB0_816
